# P8 (rwkv_out) items taken from the own XCD's row range; barriers P8|P9 and P10|P11 XCD-local, P9|P10 full again (XN overlays G/SS, HID overlays MIX)
# speedup vs baseline: 1.0191x; 1.0000x over previous
; #define LAS __attribute__((address_space(3)))
; #define lane (lane_now())
; __device__ __forceinline__ void rwkv_out_ch(const Params& p, LAS unsigned char* ldsw, int ch, int lane) {
;     const int bh = ch >> 7, c = ch & 127, b = bh >> 3, h = bh & 7, fr = lane & 15, fq = lane >> 4;
;     const h16* base = (const h16*)(p.ws + WS_SC) + ((size_t)bh * SEQ + (size_t)c * 64) * 384;
;     const bf16_t* G = (const bf16_t*)(p.ws + WS_G); const float* SS = (const float*)(p.ws + WS_SS); bf16_t* MIX = (bf16_t*)(p.ws + WS_MIX);
;     LAS bf16_t* stg = (LAS bf16_t*)ldsw;
;     bf16x8 sf[4][2]; f32x4 lg[4], lb[4];
; #pragma unroll
;     for (int nt = 0; nt < 4; ++nt) {
; #pragma unroll
;         for (int ks = 0; ks < 2; ++ks) sf[nt][ks] = *(const bf16x8*)(base + (size_t)((16 * nt + fr) * 6 + 1) * 64 + ks * 32 + fq * 8);
;         const int cc = h * 64 + 16 * fq + 4 * nt; lg[nt] = *(const f32x4*)(p.lnx_g + cc); lb[nt] = *(const f32x4*)(p.lnx_b + cc);
;     }
;     bf16x8 rbfB[2][2]; f32x4 y0B[2][4]; u32x2 gB[2][4]; h16x4 vB[2][4]; float bonB[2];
;     ...
;     RO_LOAD(0, 0);
; __global__ void __launch_bounds__(512, 2) mega_fwd(Params p) {
;     ...
;     { const int lane9 = lane; LAS unsigned char* ldsw = lds + wave * (16 * MS * 2); for (int it = gw; it < 32 * 128; it += ngw) rwkv_out_ch(p, ldsw, it, lane9); }
.LBB0_1096:
	v_readlane_b32 s0, v244, 31
	v_readlane_b32 s1, v244, 32
	s_andn2_b64 vcc, exec, s[0:1]
	s_waitcnt lgkmcnt(0)
	s_barrier
	v_mbcnt_lo_u32_b32 v0, -1, 0
	v_mbcnt_hi_u32_b32 v0, -1, v0
	s_cbranch_vccnz .LBB0_1099
	v_and_b32_e32 v6, 64, v166
	v_xor_b32_e32 v1, 16, v166
	v_add_u32_e32 v6, 64, v6
	v_cmp_lt_i32_e32 vcc, v1, v6
	s_add_u32 s0, s92, 0x4b00000
	s_mul_i32 s4, s69, 0x900
	v_cndmask_b32_e32 v1, v166, v1, vcc
	v_lshlrev_b32_e32 v151, 2, v1
	v_xor_b32_e32 v1, 32, v166
	v_cmp_lt_i32_e32 vcc, v1, v6
	v_and_b32_e32 v85, 15, v0
	v_and_b32_e32 v103, -16, v0
	v_cndmask_b32_e32 v1, v166, v1, vcc
	s_addc_u32 s1, s93, 0
	s_add_i32 s4, s4, 0
	v_ashrrev_i32_e32 v2, 4, v0
	v_lshlrev_b32_e32 v152, 2, v1
	s_movk_i32 s5, 0x90
	v_mul_u32_u24_e32 v1, 0x90, v85
	v_lshlrev_b32_e32 v6, 1, v103
	v_ashrrev_i32_e32 v66, 2, v0
	v_lshlrev_b32_e32 v0, 5, v0
	v_add3_u32 v153, s4, v1, v6
	v_mul_lo_u32 v1, v66, s5
	v_and_b32_e32 v0, 0x60, v0
	v_mul_u32_u24_e32 v3, 0x180, v85
	v_add3_u32 v154, s4, v1, v0
	v_mov_b32_e32 v1, 0
	v_lshl_add_u64 v[68:69], s[96:97], 0, v[0:1]
	v_lshlrev_b32_e32 v0, 1, v3
	v_ashrrev_i32_e32 v3, 31, v2
	v_lshlrev_b32_e32 v4, 2, v2
	v_lshlrev_b64 v[72:73], 3, v[2:3]
	v_lshlrev_b32_e32 v64, 3, v2
	v_ashrrev_i32_e32 v5, 31, v4
	v_sub_co_u32_e32 v74, vcc, 0, v72
	s_lshl_b32 s4, s68, 9
	s_mov_b32 s9, 0
	v_ashrrev_i32_e32 v65, 31, v64
	v_or_b32_e32 v150, 16, v85
	v_ashrrev_i32_e32 v67, 31, v66
	v_or_b32_e32 v155, 32, v85
	v_or_b32_e32 v156, 48, v85
	v_lshl_add_u64 v[70:71], s[6:7], 0, v[0:1]
	v_subb_co_u32_e32 v75, vcc, 0, v73, vcc
	s_add_i32 s28, s4, s86
	s_lshl_b32 s29, s94, 9
	v_mov_b32_e32 v157, 0x300
	s_mov_b64 s[6:7], 0x3000
	s_mov_b64 s[10:11], 0x6080
	s_movk_i32 s30, 0x6000
	s_mov_b64 s[12:13], 0x9080
	s_mov_b32 s31, 0x9000
	v_lshlrev_b64 v[76:77], 1, v[4:5]
	v_mov_b32_e32 v158, 0x3a27c5ac
	s_mov_b32 s34, 0x800000
	s_mov_b64 s[14:15], 0x6000
	s_mov_b64 s[16:17], 0x9000
	s_mov_b32 s35, s78
	s_mov_b32 s101, s84
	s_mov_b32 s98, 0x1000
	v_readlane_b32 s99, v244, 61
	s_cmp_eq_u32 s99, 0
	s_cbranch_scc1 .Lxo_keep
	s_lshr_b32 s99, s78, 3
	s_and_b32 s100, s99, 7
	s_lshr_b32 s99, s99, 3
	s_and_b32 s35, s100, 1
	s_lshl_b32 s35, s35, 6
	s_add_i32 s35, s35, s99
	s_lshr_b32 s100, s100, 1
	s_lshl_b32 s100, s100, 3
	s_and_b32 s99, s78, 7
	s_add_i32 s100, s100, s99
	s_lshl_b32 s100, s100, 7
	s_add_i32 s35, s35, s100
	s_lshl_b32 s28, s35, 6
	s_movk_i32 s29, 0x800
	s_movk_i32 s84, 32
	s_add_i32 s98, s35, 64
.Lxo_keep:
.LBB0_1098:
	s_ashr_i32 s18, s35, 7
	s_ashr_i32 s20, s35, 10
	s_ashr_i32 s19, s18, 31
	s_and_b32 s8, s28, 0x1fc0
	s_ashr_i32 s21, s20, 31
	s_lshl_b64 s[26:27], s[18:19], 13
	s_lshl_b32 s4, s18, 6
	v_or_b32_e32 v0, s8, v85
	s_lshl_b64 s[20:21], s[20:21], 13
	s_or_b32 s18, s26, s8
	s_mul_i32 s22, s27, 0x300
	v_or_b32_e32 v36, s20, v0
	v_or_b32_e32 v38, s26, v0
	v_mad_u64_u32 v[0:1], s[18:19], s18, v157, v[70:71]
	s_and_b32 s4, s4, 0x1c0
	v_add_u32_e32 v1, s22, v1
	v_or_b32_e32 v8, s8, v150
	v_add_u32_e32 v2, s4, v103
	s_lshl_b32 s4, s4, 1
	v_mov_b32_e32 v39, s27
	v_lshl_add_u64 v[40:41], v[64:65], 1, v[0:1]
	v_mov_b32_e32 v37, s21
	v_lshl_add_u64 v[6:7], v[38:39], 4, s[0:1]
	s_add_u32 s18, s2, s4
	v_or_b32_e32 v38, s26, v8
	v_add_co_u32_e32 v56, vcc, s30, v40
	s_mov_b32 s23, s9
	v_or_b32_e32 v12, s8, v155
	v_lshl_add_u64 v[78:79], s[20:21], 0, v[66:67]
	v_ashrrev_i32_e32 v3, 31, v2
	v_lshlrev_b64 v[4:5], 10, v[36:37]
	v_or_b32_e32 v36, s20, v8
	s_addc_u32 s19, s3, 0
	v_lshl_add_u64 v[8:9], v[38:39], 4, s[0:1]
	s_or_b32 s22, s8, 16
	v_addc_co_u32_e32 v57, vcc, 0, v41, vcc
	s_mov_b32 s5, s9
	s_mov_b32 s25, s9
	v_or_b32_e32 v13, s8, v156
	v_lshl_add_u64 v[10:11], v[78:79], 0, s[8:9]
	v_lshlrev_b64 v[2:3], 2, v[2:3]
	v_lshl_add_u64 v[4:5], s[2:3], 0, v[4:5]
	global_load_dword v84, v[6:7], off offset:8
	global_load_dword v102, v[8:9], off offset:8
	v_lshlrev_b64 v[6:7], 10, v[36:37]
	v_or_b32_e32 v36, s20, v12
	v_or_b32_e32 v38, s26, v12
	s_or_b32 s24, s8, 32
	v_lshl_add_u64 v[52:53], v[78:79], 0, s[22:23]
	v_add_co_u32_e32 v100, vcc, s31, v40
	v_lshl_add_u64 v[106:107], v[40:41], 0, v[74:75]
	v_lshl_add_u64 v[80:81], v[68:69], 0, s[4:5]
	v_lshlrev_b64 v[10:11], 11, v[10:11]
	v_lshl_add_u64 v[16:17], s[58:59], 0, v[2:3]
	v_lshl_add_u64 v[28:29], s[60:61], 0, v[2:3]
	v_lshl_add_u64 v[42:43], v[4:5], 0, s[4:5]
	v_lshl_add_u64 v[44:45], s[18:19], 0, v[6:7]
	v_lshlrev_b64 v[46:47], 10, v[36:37]
	v_lshl_add_u64 v[86:87], v[38:39], 4, s[0:1]
	v_or_b32_e32 v36, s20, v13
	v_or_b32_e32 v38, s26, v13
	v_lshl_add_u64 v[54:55], v[78:79], 0, s[24:25]
	v_lshl_add_u64 v[82:83], v[40:41], 0, s[6:7]
	v_lshl_add_u64 v[96:97], v[40:41], 0, s[10:11]
	v_addc_co_u32_e32 v101, vcc, 0, v41, vcc
	v_lshlrev_b64 v[112:113], 11, v[52:53]
	v_lshl_add_u64 v[120:121], v[106:107], 0, v[72:73]
	v_lshl_add_u64 v[92:93], v[80:81], 0, v[10:11]
	global_load_dwordx4 v[48:51], v[40:41], off offset:128
	global_load_dwordx4 v[32:35], v[40:41], off offset:192
	global_load_dwordx4 v[0:3], v[16:17], off offset:48
	global_load_dwordx4 v[4:7], v[16:17], off offset:32
	global_load_dwordx4 v[12:15], v[16:17], off offset:16
	global_load_dwordx4 v[20:23], v[16:17], off
	global_load_dwordx4 v[8:11], v[28:29], off offset:48
	s_nop 0
	global_load_dwordx4 v[16:19], v[28:29], off offset:32
	global_load_dwordx4 v[24:27], v[28:29], off offset:16
	s_nop 0
	global_load_dwordx4 v[28:31], v[28:29], off
	v_lshl_add_u64 v[98:99], v[40:41], 0, s[12:13]
	global_load_dwordx4 v[160:163], v[40:41], off offset:256
	global_load_dwordx4 v[168:171], v[40:41], off offset:320
	global_load_dwordx4 v[132:135], v[40:41], off offset:384
	v_lshl_add_u64 v[104:105], v[42:43], 0, v[76:77]
; __device__ __forceinline__ void rwkv_out_ch(const Params& p, LAS unsigned char* ldsw, int ch, int lane) {
;     ...
;     RO_LOAD(0, 0);
; #pragma unroll
;     for (int ts = 0; ts < 4; ++ts) {
;         const int sl = ts & 1;
;         if (ts < 3) RO_LOAD(sl ^ 1, ts + 1);
;         f32x4 acc[4];
; #pragma unroll
;         for (int nt = 0; nt < 4; ++nt) acc[nt] = y0B[sl][nt];
; #pragma unroll
;         for (int nt = 0; nt < 4; ++nt)
; #pragma unroll
;             for (int ks = 0; ks < 2; ++ks) acc[nt] = __builtin_amdgcn_mfma_f32_16x16x32_bf16(sf[nt][ks], rbfB[sl][ks], acc[nt], 0, 0, 0);
	v_lshl_add_u64 v[110:111], v[44:45], 0, v[76:77]
	v_lshl_add_u64 v[94:95], v[40:41], 0, s[14:15]
	v_lshl_add_u64 v[108:109], s[18:19], 0, v[46:47]
	v_lshl_add_u64 v[90:91], v[40:41], 0, s[16:17]
	v_lshlrev_b64 v[114:115], 10, v[36:37]
	v_lshl_add_u64 v[88:89], v[38:39], 4, s[0:1]
	v_lshlrev_b64 v[116:117], 11, v[54:55]
	global_load_dwordx4 v[60:63], v[82:83], off offset:128
	global_load_dwordx4 v[40:43], v[82:83], off offset:192
	s_nop 0
	global_load_dwordx4 v[56:59], v[56:57], off offset:128
	s_nop 0
	global_load_dwordx4 v[36:39], v[98:99], off offset:64
	global_load_dwordx4 v[52:55], v[100:101], off offset:128
	global_load_dwordx2 v[118:119], v[104:105], off
	global_load_dwordx2 v[122:123], v[106:107], off offset:640
	global_load_dwordx2 v[124:125], v[104:105], off offset:32
	global_load_dwordx2 v[126:127], v[104:105], off offset:64
	global_load_dwordx2 v[128:129], v[104:105], off offset:96
	global_load_dwordx4 v[172:175], v[82:83], off offset:256
	global_load_dwordx4 v[176:179], v[82:83], off offset:320
	global_load_dwordx4 v[44:47], v[96:97], off offset:64
	global_load_dwordx4 v[136:139], v[82:83], off offset:384
	v_lshl_add_u64 v[96:97], v[82:83], 0, v[74:75]
	v_lshl_add_u64 v[100:101], v[80:81], 0, v[112:113]
	v_lshl_add_u64 v[112:113], v[120:121], 0, v[74:75]
	v_lshl_add_u64 v[106:107], s[18:19], 0, v[114:115]
	v_lshl_add_u64 v[82:83], v[80:81], 0, v[116:117]
	v_lshl_add_u64 v[114:115], v[96:97], 0, v[72:73]
	v_lshl_add_u64 v[116:117], v[112:113], 0, v[72:73]
	global_load_dwordx2 v[148:149], v[110:111], off
	global_load_dwordx2 v[164:165], v[110:111], off offset:32
	global_load_dwordx2 v[212:213], v[110:111], off offset:64
	global_load_dwordx2 v[214:215], v[96:97], off offset:640
	global_load_dwordx2 v[216:217], v[110:111], off offset:96
	global_load_dwordx4 v[144:147], v[120:121], off offset:448
	global_load_dwordx2 v[218:219], v[112:113], off offset:672
	global_load_dwordx4 v[180:183], v[114:115], off offset:448
	global_load_dwordx4 v[184:187], v[116:117], off offset:512
	v_lshl_add_u64 v[114:115], v[114:115], 0, v[74:75]
	v_lshl_add_u64 v[116:117], v[116:117], 0, v[74:75]
	global_load_dwordx2 v[220:221], v[114:115], off offset:672
	v_lshl_add_u64 v[114:115], v[114:115], 0, v[72:73]
	global_load_dwordx4 v[188:191], v[114:115], off offset:512
	global_load_dwordx2 v[222:223], v[116:117], off offset:704
	v_lshl_add_u64 v[116:117], v[116:117], 0, v[72:73]
	v_lshl_add_u64 v[114:115], v[114:115], 0, v[74:75]
	global_load_dwordx4 v[192:195], v[116:117], off offset:576
	global_load_dwordx2 v[224:225], v[114:115], off offset:704
	v_lshl_add_u64 v[114:115], v[114:115], 0, v[72:73]
	v_lshl_add_u64 v[116:117], v[116:117], 0, v[74:75]
	global_load_dwordx4 v[196:199], v[114:115], off offset:576
	global_load_dwordx2 v[226:227], v[116:117], off offset:736
	v_lshl_add_u64 v[114:115], v[114:115], 0, v[74:75]
	global_load_dwordx2 v[228:229], v[114:115], off offset:736
	s_waitcnt vmcnt(31)
	v_mfma_f32_16x16x32_bf16 v[200:203], v[48:51], v[160:163], v[132:135]
	v_lshl_add_u64 v[104:105], v[108:109], 0, v[76:77]
	v_lshl_add_u64 v[108:109], v[94:95], 0, v[74:75]
	s_waitcnt vmcnt(24)
	v_cvt_f32_f16_e32 v140, v122
	s_waitcnt vmcnt(17)
	v_mfma_f32_16x16x32_bf16 v[204:207], v[48:51], v[172:175], v[136:139]
	v_lshlrev_b32_e32 v114, 16, v118
	v_and_b32_e32 v115, 0xffff0000, v118
	v_lshlrev_b32_e32 v116, 16, v119
	s_waitcnt vmcnt(11)
	v_mfma_f32_16x16x32_bf16 v[208:211], v[60:63], v[160:163], v[144:147]
	v_and_b32_e32 v117, 0xffff0000, v119
	v_cvt_f32_f16_sdwa v141, v122 dst_sel:DWORD dst_unused:UNUSED_PAD src0_sel:WORD_1
	v_cvt_f32_f16_e32 v142, v123
	s_waitcnt vmcnt(9)
	v_mfma_f32_16x16x32_bf16 v[180:183], v[60:63], v[172:175], v[180:183]
	v_cvt_f32_f16_sdwa v143, v123 dst_sel:DWORD dst_unused:UNUSED_PAD src0_sel:WORD_1
	v_lshlrev_b32_e32 v118, 16, v124
	v_and_b32_e32 v119, 0xffff0000, v124
	s_waitcnt vmcnt(8)
	v_mfma_f32_16x16x32_bf16 v[184:187], v[56:59], v[160:163], v[184:187]
	v_lshlrev_b32_e32 v122, 16, v125
	v_and_b32_e32 v123, 0xffff0000, v125
	v_lshlrev_b32_e32 v124, 16, v128
	s_waitcnt vmcnt(6)
	v_mfma_f32_16x16x32_bf16 v[188:191], v[56:59], v[172:175], v[188:191]
	v_and_b32_e32 v125, 0xffff0000, v128
	v_lshlrev_b32_e32 v130, 16, v129
	v_and_b32_e32 v131, 0xffff0000, v129
	s_waitcnt vmcnt(4)
	v_mfma_f32_16x16x32_bf16 v[160:163], v[52:55], v[160:163], v[192:195]
	v_lshlrev_b32_e32 v128, 16, v148
	v_and_b32_e32 v129, 0xffff0000, v148
	v_lshlrev_b32_e32 v134, 16, v149
	s_waitcnt vmcnt(2)
; __device__ __forceinline__ void rwkv_out_ch(const Params& p, LAS unsigned char* ldsw, int ch, int lane) {
;     ...
;         for (int nt = 0; nt < 4; ++nt)
; #pragma unroll
;             for (int ks = 0; ks < 2; ++ks) acc[nt] = __builtin_amdgcn_mfma_f32_16x16x32_bf16(sf[nt][ks], rbfB[sl][ks], acc[nt], 0, 0, 0);
;         float s_ = 0.f;
; #pragma unroll
;         for (int nt = 0; nt < 4; ++nt) s_ += (acc[nt].x + acc[nt].y) + (acc[nt].z + acc[nt].w);
;         s_ += __shfl_xor(s_, 16); s_ += __shfl_xor(s_, 32);
;         const float mean = s_ * (1.f / 64.f); float q = 0.f;
; #pragma unroll
;         for (int nt = 0; nt < 4; ++nt) { acc[nt] = acc[nt] - mean; q += (acc[nt].x * acc[nt].x + acc[nt].y * acc[nt].y) + (acc[nt].z * acc[nt].z + acc[nt].w * acc[nt].w); }
;         q += __shfl_xor(q, 16); q += __shfl_xor(q, 32);
;         const float rstd = rsqrtf(q * (1.f / 64.f) + 64e-5f), bon = bonB[sl];
	v_mfma_f32_16x16x32_bf16 v[172:175], v[52:55], v[172:175], v[196:199]
	v_and_b32_e32 v135, 0xffff0000, v149
	v_lshlrev_b32_e32 v132, 16, v164
	v_and_b32_e32 v133, 0xffff0000, v164
	v_mfma_f32_16x16x32_bf16 v[192:195], v[32:35], v[168:171], v[200:203]
	v_lshlrev_b32_e32 v138, 16, v165
	v_and_b32_e32 v139, 0xffff0000, v165
	v_lshlrev_b32_e32 v136, 16, v212
	v_mfma_f32_16x16x32_bf16 v[196:199], v[32:35], v[176:179], v[204:207]
	v_and_b32_e32 v137, 0xffff0000, v212
	v_lshlrev_b32_e32 v144, 16, v213
	v_and_b32_e32 v145, 0xffff0000, v213
	v_mfma_f32_16x16x32_bf16 v[200:203], v[40:43], v[168:171], v[208:211]
	v_cvt_f32_f16_e32 v164, v214
	v_cvt_f32_f16_sdwa v165, v214 dst_sel:DWORD dst_unused:UNUSED_PAD src0_sel:WORD_1
	v_cvt_f32_f16_e32 v212, v215
	v_mfma_f32_16x16x32_bf16 v[180:183], v[40:43], v[176:179], v[180:183]
	v_cvt_f32_f16_sdwa v213, v215 dst_sel:DWORD dst_unused:UNUSED_PAD src0_sel:WORD_1
	s_nop 2
	v_mov_b32_e32 v230, v200
	v_mov_b32_e32 v231, v203
	v_mfma_f32_16x16x32_bf16 v[184:187], v[44:47], v[168:171], v[184:187]
	v_lshlrev_b32_e32 v146, 16, v216
	v_mov_b32_e32 v236, v180
	v_mov_b32_e32 v237, v183
	v_mfma_f32_16x16x32_bf16 v[188:191], v[44:47], v[176:179], v[188:191]
	v_and_b32_e32 v147, 0xffff0000, v216
	s_nop 2
	v_add_f32_e32 v232, v184, v185
	v_add_f32_e32 v234, v186, v187
	v_mfma_f32_16x16x32_bf16 v[160:163], v[36:39], v[168:171], v[160:163]
	v_lshlrev_b32_e32 v148, 16, v217
	v_add_f32_e32 v238, v188, v189
	v_add_f32_e32 v240, v190, v191
	v_mfma_f32_16x16x32_bf16 v[168:171], v[36:39], v[176:179], v[172:175]
	v_mov_b32_e32 v176, v197
	v_mov_b32_e32 v177, v198
	v_mov_b32_e32 v178, v196
	v_mov_b32_e32 v172, v193
	v_mov_b32_e32 v173, v194
	v_mov_b32_e32 v174, v192
	v_mov_b32_e32 v175, v195
	v_mov_b32_e32 v179, v199
	v_pk_add_f32 v[172:173], v[172:173], v[174:175]
	v_mov_b32_e32 v174, v201
	v_mov_b32_e32 v175, v202
	v_pk_add_f32 v[176:177], v[176:177], v[178:179]
	v_mov_b32_e32 v178, v181
	v_mov_b32_e32 v179, v182
	v_add_f32_e32 v159, v172, v173
	v_pk_add_f32 v[172:173], v[174:175], v[230:231]
	v_add_f32_e32 v167, v176, v177
	v_pk_add_f32 v[176:177], v[178:179], v[236:237]
	v_pk_add_f32 v[172:173], v[172:173], v[172:173] op_sel:[0,1] op_sel_hi:[1,0]
	v_pk_add_f32 v[176:177], v[176:177], v[176:177] op_sel:[0,1] op_sel_hi:[1,0]
	v_mov_b32_e32 v175, v160
	v_mov_b32_e32 v233, v162
	v_mov_b32_e32 v235, v163
	v_add_f32_e32 v174, 0, v159
	v_add_f32_e32 v230, 0, v167
	v_mov_b32_e32 v231, v168
	v_mov_b32_e32 v239, v170
	v_mov_b32_e32 v241, v171
	v_mov_b32_e32 v173, v161
	v_mov_b32_e32 v177, v169
	v_pk_add_f32 v[178:179], v[232:233], v[234:235]
	v_pk_add_f32 v[232:233], v[238:239], v[240:241]
	v_pk_add_f32 v[172:173], v[174:175], v[172:173]
	v_pk_add_f32 v[174:175], v[230:231], v[176:177]
	v_pk_add_f32 v[172:173], v[172:173], v[178:179]
	v_pk_add_f32 v[174:175], v[174:175], v[232:233]
	v_add_f32_e32 v159, v172, v173
	v_add_f32_e32 v167, v174, v175
	ds_bpermute_b32 v172, v151, v159
	ds_bpermute_b32 v173, v151, v167
	v_and_b32_e32 v149, 0xffff0000, v217
	v_cvt_f32_f16_e32 v214, v218
	v_cvt_f32_f16_sdwa v215, v218 dst_sel:DWORD dst_unused:UNUSED_PAD src0_sel:WORD_1
	s_waitcnt lgkmcnt(1)
	v_add_f32_e32 v159, v159, v172
	s_waitcnt lgkmcnt(0)
	v_add_f32_e32 v167, v167, v173
	ds_bpermute_b32 v172, v152, v159
	ds_bpermute_b32 v173, v152, v167
	v_cvt_f32_f16_e32 v216, v219
	v_cvt_f32_f16_sdwa v217, v219 dst_sel:DWORD dst_unused:UNUSED_PAD src0_sel:WORD_1
	v_cvt_f32_f16_e32 v218, v220
	s_waitcnt lgkmcnt(1)
	v_add_f32_e32 v159, v159, v172
	s_waitcnt lgkmcnt(0)
	v_add_f32_e32 v167, v167, v173
	v_fmamk_f32 v173, v159, 0xbc800000, v193
	v_fmamk_f32 v172, v159, 0xbc800000, v192
	v_fmamk_f32 v195, v159, 0xbc800000, v195
	v_fmac_f32_e32 v194, 0xbc800000, v159
	v_fmamk_f32 v175, v159, 0xbc800000, v201
	v_fmamk_f32 v174, v159, 0xbc800000, v200
	v_fmamk_f32 v203, v159, 0xbc800000, v203
	v_fmac_f32_e32 v202, 0xbc800000, v159
	v_fmamk_f32 v179, v167, 0xbc800000, v197
	v_fmamk_f32 v178, v167, 0xbc800000, v196
	v_fmamk_f32 v199, v167, 0xbc800000, v199
	v_fmac_f32_e32 v198, 0xbc800000, v167
	v_fmamk_f32 v177, v159, 0xbc800000, v185
	v_fmamk_f32 v176, v159, 0xbc800000, v184
	v_pk_mul_f32 v[184:185], v[194:195], v[194:195]
	v_pk_mul_f32 v[192:193], v[172:173], v[172:173]
	v_pk_mul_f32 v[196:197], v[202:203], v[202:203]
	v_pk_mul_f32 v[200:201], v[174:175], v[174:175]
	v_pk_mul_f32 v[230:231], v[198:199], v[198:199]
	v_pk_mul_f32 v[232:233], v[178:179], v[178:179]
	v_fmac_f32_e32 v186, 0xbc800000, v159
	v_pk_mov_b32 v[238:239], v[192:193], v[184:185] op_sel:[1,0]
	v_mov_b32_e32 v193, v185
	v_pk_mov_b32 v[184:185], v[200:201], v[196:197] op_sel:[1,0]
	v_mov_b32_e32 v201, v197
	v_pk_mov_b32 v[196:197], v[232:233], v[230:231] op_sel:[1,0]
	v_mov_b32_e32 v233, v231
	v_fmamk_f32 v187, v159, 0xbc800000, v187
	v_fmamk_f32 v181, v167, 0xbc800000, v181
	v_fmamk_f32 v180, v167, 0xbc800000, v180
	v_fmamk_f32 v183, v167, 0xbc800000, v183
	v_fmac_f32_e32 v182, 0xbc800000, v167
	v_pk_add_f32 v[184:185], v[184:185], v[200:201]
	v_mul_f32_e32 v200, v176, v176
	v_pk_add_f32 v[196:197], v[196:197], v[232:233]
	v_mul_f32_e32 v232, v186, v186
	v_fmamk_f32 v161, v159, 0xbc800000, v161
	v_fmac_f32_e32 v160, 0xbc800000, v159
	v_pk_mul_f32 v[234:235], v[182:183], v[182:183]
	v_pk_mul_f32 v[236:237], v[180:181], v[180:181]
	v_pk_add_f32 v[192:193], v[238:239], v[192:193]
	v_pk_fma_f32 v[200:201], v[176:177], v[176:177], v[200:201] op_sel_hi:[1,1,0]
	v_pk_fma_f32 v[232:233], v[186:187], v[186:187], v[232:233] op_sel_hi:[1,1,0]
	v_fmamk_f32 v163, v159, 0xbc800000, v163
	v_fmamk_f32 v162, v159, 0xbc800000, v162
	v_pk_mov_b32 v[230:231], v[236:237], v[234:235] op_sel:[1,0]
	v_mov_b32_e32 v237, v235
; #define LAS __attribute__((address_space(3)))
; #define LDS_WAIT() asm volatile("s_waitcnt lgkmcnt(0)" ::: "memory")
; __device__ __forceinline__ float bflo(unsigned w) { return __uint_as_float(w << 16); }
; __device__ __forceinline__ float bfhi(unsigned w) { return __uint_as_float(w & 0xffff0000u); }
; __device__ __forceinline__ void st_bf4(LAS bf16_t* p, f32x4 v) { u32x2 w; w.x = pk2(v.x, v.y); w.y = pk2(v.z, v.w); *(LAS u32x2*)p = w; }
; #define lane (lane_now())
; __device__ __forceinline__ void rwkv_out_ch(const Params& p, LAS unsigned char* ldsw, int ch, int lane) {
;     ...
;         float s_ = 0.f;
; #pragma unroll
;         for (int nt = 0; nt < 4; ++nt) s_ += (acc[nt].x + acc[nt].y) + (acc[nt].z + acc[nt].w);
;         s_ += __shfl_xor(s_, 16); s_ += __shfl_xor(s_, 32);
;         const float mean = s_ * (1.f / 64.f); float q = 0.f;
; #pragma unroll
;         for (int nt = 0; nt < 4; ++nt) { acc[nt] = acc[nt] - mean; q += (acc[nt].x * acc[nt].x + acc[nt].y * acc[nt].y) + (acc[nt].z * acc[nt].z + acc[nt].w * acc[nt].w); }
;         q += __shfl_xor(q, 16); q += __shfl_xor(q, 32);
;         const float rstd = rsqrtf(q * (1.f / 64.f) + 64e-5f), bon = bonB[sl];
; #pragma unroll
;         for (int nt = 0; nt < 4; ++nt) {
;             const u32x2 gw = gB[sl][nt]; const h16x4 v4 = vB[sl][nt];
;             const f32x4 g = {bflo(gw.x), bfhi(gw.x), bflo(gw.y), bfhi(gw.y)}, vv = {(float)v4[0], (float)v4[1], (float)v4[2], (float)v4[3]};
;             st_bf4(stg + fr * MS + 16 * fq + 4 * nt, (acc[nt] * rstd * lg[nt] + lb[nt] + vv * bon) * g);
;         }
;         LDS_WAIT();
;         {
;             const int row = lane >> 2, pc = (lane & 3) * 16;
;             const u32x4 w0 = *(const LAS u32x4*)(stg + row * MS + pc), w1 = *(const LAS u32x4*)(stg + row * MS + pc + 8);
;             bf16_t* dst = MIX + ((size_t)b * SEQ + c * 64 + 16 * ts + row) * DM + h * 64 + pc;
;             *(u32x4*)dst = w0; *(u32x4*)(dst + 8) = w1;
;         }
	v_fmamk_f32 v188, v167, 0xbc800000, v188
	v_fmac_f32_e32 v190, 0xbc800000, v167
	v_mul_f32_e32 v200, v160, v160
	v_mul_f32_e32 v232, v161, v161
	v_pk_add_f32 v[192:193], v[192:193], v[192:193] op_sel_hi:[0,1]
	v_pk_add_f32 v[184:185], v[184:185], v[184:185] op_sel_hi:[0,1]
	v_fmamk_f32 v189, v167, 0xbc800000, v189
	v_fmamk_f32 v191, v167, 0xbc800000, v191
	v_pk_add_f32 v[230:231], v[230:231], v[236:237]
	v_mul_f32_e32 v236, v188, v188
	v_pk_add_f32 v[200:201], v[200:201], v[232:233]
	v_mul_f32_e32 v232, v190, v190
	v_mul_f32_e32 v192, v162, v162
	v_mul_f32_e32 v184, v163, v163
	v_fmamk_f32 v169, v167, 0xbc800000, v169
	v_fmac_f32_e32 v168, 0xbc800000, v167
	v_pk_fma_f32 v[236:237], v[188:189], v[188:189], v[236:237] op_sel_hi:[1,1,0]
	v_pk_fma_f32 v[232:233], v[190:191], v[190:191], v[232:233] op_sel_hi:[1,1,0]
	v_pk_add_f32 v[184:185], v[192:193], v[184:185]
	v_fmamk_f32 v171, v167, 0xbc800000, v171
	v_fmamk_f32 v170, v167, 0xbc800000, v170
	v_pk_add_f32 v[192:193], v[196:197], v[196:197] op_sel_hi:[0,1]
	v_pk_add_f32 v[196:197], v[230:231], v[230:231] op_sel_hi:[0,1]
	v_mul_f32_e32 v236, v168, v168
	v_mul_f32_e32 v232, v169, v169
	v_mul_f32_e32 v192, v170, v170
	v_mul_f32_e32 v196, v171, v171
	v_pk_add_f32 v[232:233], v[236:237], v[232:233]
	v_pk_add_f32 v[192:193], v[192:193], v[196:197]
	v_pk_add_f32 v[184:185], v[200:201], v[184:185]
	v_pk_add_f32 v[192:193], v[232:233], v[192:193]
	v_add_f32_e32 v159, v184, v185
	v_add_f32_e32 v167, v192, v193
	ds_bpermute_b32 v192, v151, v159
	v_cvt_f32_f16_sdwa v219, v220 dst_sel:DWORD dst_unused:UNUSED_PAD src0_sel:WORD_1
	v_cvt_f32_f16_e32 v204, v221
	v_cvt_f32_f16_sdwa v205, v221 dst_sel:DWORD dst_unused:UNUSED_PAD src0_sel:WORD_1
	v_cvt_f32_f16_e32 v206, v222
	s_waitcnt lgkmcnt(0)
	v_add_f32_e32 v159, v159, v192
	ds_bpermute_b32 v192, v151, v167
	v_cvt_f32_f16_sdwa v207, v222 dst_sel:DWORD dst_unused:UNUSED_PAD src0_sel:WORD_1
	v_cvt_f32_f16_e32 v208, v223
	v_cvt_f32_f16_sdwa v209, v223 dst_sel:DWORD dst_unused:UNUSED_PAD src0_sel:WORD_1
	v_cvt_f32_f16_e32 v210, v224
	s_waitcnt lgkmcnt(0)
	v_add_f32_e32 v167, v167, v192
	ds_bpermute_b32 v192, v152, v159
	v_cvt_f32_f16_sdwa v211, v224 dst_sel:DWORD dst_unused:UNUSED_PAD src0_sel:WORD_1
	v_cvt_f32_f16_e32 v220, v225
	v_cvt_f32_f16_sdwa v221, v225 dst_sel:DWORD dst_unused:UNUSED_PAD src0_sel:WORD_1
	s_waitcnt vmcnt(1)
	v_cvt_f32_f16_e32 v222, v226
	s_waitcnt lgkmcnt(0)
	v_add_f32_e32 v159, v159, v192
	ds_bpermute_b32 v192, v152, v167
	v_fmamk_f32 v159, v159, 0x3c800000, v158
	v_cmp_gt_f32_e32 vcc, s34, v159
	v_cvt_f32_f16_sdwa v223, v226 dst_sel:DWORD dst_unused:UNUSED_PAD src0_sel:WORD_1
	v_cvt_f32_f16_e32 v224, v227
	s_waitcnt lgkmcnt(0)
	v_add_f32_e32 v167, v167, v192
	v_mul_f32_e32 v192, 0x4b800000, v159
	v_cndmask_b32_e32 v159, v159, v192, vcc
	v_rsq_f32_e32 v159, v159
	v_fmamk_f32 v167, v167, 0x3c800000, v158
	v_mul_f32_e32 v192, 0x4b800000, v167
	v_cmp_gt_f32_e64 s[4:5], s34, v167
	v_cvt_f32_f16_sdwa v225, v227 dst_sel:DWORD dst_unused:UNUSED_PAD src0_sel:WORD_1
	v_lshlrev_b32_e32 v120, 16, v126
	v_cndmask_b32_e64 v167, v167, v192, s[4:5]
	v_mul_f32_e32 v192, 0x45800000, v159
	v_cndmask_b32_e32 v192, v159, v192, vcc
	v_rsq_f32_e32 v159, v167
	v_pk_mul_f32 v[194:195], v[194:195], v[192:193] op_sel_hi:[1,0]
	v_pk_mul_f32 v[202:203], v[202:203], v[192:193] op_sel_hi:[1,0]
	v_pk_mul_f32 v[172:173], v[172:173], v[192:193] op_sel_hi:[1,0]
	v_mul_f32_e32 v167, 0x45800000, v159
	v_cndmask_b32_e64 v242, v159, v167, s[4:5]
	v_pk_mul_f32 v[174:175], v[174:175], v[192:193] op_sel_hi:[1,0]
	v_pk_mul_f32 v[186:187], v[186:187], v[192:193] op_sel_hi:[1,0]
	v_pk_mul_f32 v[160:161], v[160:161], v[192:193] op_sel_hi:[1,0]
	v_pk_mul_f32 v[176:177], v[176:177], v[192:193] op_sel_hi:[1,0]
	v_pk_mul_f32 v[162:163], v[162:163], v[192:193] op_sel_hi:[1,0]
	v_pk_mul_f32 v[192:193], v[198:199], v[242:243] op_sel_hi:[1,0]
	v_pk_fma_f32 v[194:195], v[22:23], v[194:195], v[30:31]
	v_pk_fma_f32 v[172:173], v[20:21], v[172:173], v[28:29]
	v_pk_fma_f32 v[198:199], v[14:15], v[202:203], v[26:27]
	v_pk_fma_f32 v[174:175], v[12:13], v[174:175], v[24:25]
	v_pk_fma_f32 v[186:187], v[6:7], v[186:187], v[18:19]
	v_pk_fma_f32 v[176:177], v[4:5], v[176:177], v[16:17]
	v_pk_fma_f32 v[162:163], v[2:3], v[162:163], v[10:11]
	v_pk_fma_f32 v[160:161], v[0:1], v[160:161], v[8:9]
	v_pk_fma_f32 v[140:141], v[140:141], v[84:85], v[172:173] op_sel_hi:[1,0,1]
	v_pk_fma_f32 v[142:143], v[142:143], v[84:85], v[194:195] op_sel_hi:[1,0,1]
	v_pk_fma_f32 v[172:173], v[214:215], v[84:85], v[174:175] op_sel_hi:[1,0,1]
	v_pk_fma_f32 v[174:175], v[216:217], v[84:85], v[198:199] op_sel_hi:[1,0,1]
	v_and_b32_e32 v121, 0xffff0000, v126
	v_lshlrev_b32_e32 v126, 16, v127
	v_and_b32_e32 v127, 0xffff0000, v127
	v_pk_fma_f32 v[176:177], v[84:85], v[206:207], v[176:177] op_sel_hi:[0,1,1]
	v_pk_fma_f32 v[186:187], v[84:85], v[208:209], v[186:187] op_sel_hi:[0,1,1]
	v_pk_fma_f32 v[160:161], v[84:85], v[222:223], v[160:161] op_sel_hi:[0,1,1]
	v_pk_fma_f32 v[162:163], v[84:85], v[224:225], v[162:163] op_sel_hi:[0,1,1]
	v_pk_mul_f32 v[116:117], v[142:143], v[116:117]
	v_pk_mul_f32 v[114:115], v[140:141], v[114:115]
	v_pk_mul_f32 v[122:123], v[174:175], v[122:123]
	v_pk_mul_f32 v[118:119], v[172:173], v[118:119]
	v_pk_mul_f32 v[126:127], v[186:187], v[126:127]
	v_pk_mul_f32 v[120:121], v[176:177], v[120:121]
	v_pk_mul_f32 v[130:131], v[162:163], v[130:131]
	v_pk_mul_f32 v[124:125], v[160:161], v[124:125]
	v_cvt_pk_bf16_f32 v114, v114, v115
	v_cvt_pk_bf16_f32 v115, v116, v117
	v_cvt_pk_bf16_f32 v116, v118, v119
	v_cvt_pk_bf16_f32 v117, v122, v123
	v_cvt_pk_bf16_f32 v118, v120, v121
	v_cvt_pk_bf16_f32 v119, v126, v127
	v_cvt_pk_bf16_f32 v120, v124, v125
	v_cvt_pk_bf16_f32 v121, v130, v131
	ds_write_b128 v153, v[114:117]
	ds_write_b128 v153, v[118:121] offset:16
	s_waitcnt lgkmcnt(0)
; #define LAS __attribute__((address_space(3)))
; #define LDS_WAIT() asm volatile("s_waitcnt lgkmcnt(0)" ::: "memory")
; __device__ __forceinline__ float bflo(unsigned w) { return __uint_as_float(w << 16); }
; __device__ __forceinline__ float bfhi(unsigned w) { return __uint_as_float(w & 0xffff0000u); }
; #define lane (lane_now())
; __device__ __forceinline__ void rwkv_out_ch(const Params& p, LAS unsigned char* ldsw, int ch, int lane) {
;     ...
;     RO_LOAD(0, 0);
; #pragma unroll
;     for (int ts = 0; ts < 4; ++ts) {
;         const int sl = ts & 1;
;         if (ts < 3) RO_LOAD(sl ^ 1, ts + 1);
;         f32x4 acc[4];
; #pragma unroll
;         for (int nt = 0; nt < 4; ++nt) acc[nt] = y0B[sl][nt];
; #pragma unroll
;         for (int nt = 0; nt < 4; ++nt)
; #pragma unroll
;             for (int ks = 0; ks < 2; ++ks) acc[nt] = __builtin_amdgcn_mfma_f32_16x16x32_bf16(sf[nt][ks], rbfB[sl][ks], acc[nt], 0, 0, 0);
;         float s_ = 0.f;
; #pragma unroll
;         for (int nt = 0; nt < 4; ++nt) s_ += (acc[nt].x + acc[nt].y) + (acc[nt].z + acc[nt].w);
;         s_ += __shfl_xor(s_, 16); s_ += __shfl_xor(s_, 32);
;         const float mean = s_ * (1.f / 64.f); float q = 0.f;
; #pragma unroll
;         for (int nt = 0; nt < 4; ++nt) { acc[nt] = acc[nt] - mean; q += (acc[nt].x * acc[nt].x + acc[nt].y * acc[nt].y) + (acc[nt].z * acc[nt].z + acc[nt].w * acc[nt].w); }
;         q += __shfl_xor(q, 16); q += __shfl_xor(q, 32);
;         const float rstd = rsqrtf(q * (1.f / 64.f) + 64e-5f), bon = bonB[sl];
; #pragma unroll
;         for (int nt = 0; nt < 4; ++nt) {
;             const u32x2 gw = gB[sl][nt]; const h16x4 v4 = vB[sl][nt];
;             const f32x4 g = {bflo(gw.x), bfhi(gw.x), bflo(gw.y), bfhi(gw.y)}, vv = {(float)v4[0], (float)v4[1], (float)v4[2], (float)v4[3]};
;             st_bf4(stg + fr * MS + 16 * fq + 4 * nt, (acc[nt] * rstd * lg[nt] + lb[nt] + vv * bon) * g);
;         }
;         LDS_WAIT();
;         {
;             const int row = lane >> 2, pc = (lane & 3) * 16;
;             const u32x4 w0 = *(const LAS u32x4*)(stg + row * MS + pc), w1 = *(const LAS u32x4*)(stg + row * MS + pc + 8);
;             bf16_t* dst = MIX + ((size_t)b * SEQ + c * 64 + 16 * ts + row) * DM + h * 64 + pc;
;             *(u32x4*)dst = w0; *(u32x4*)(dst + 8) = w1;
;         }
;         LDS_WAIT();
;     }
	s_waitcnt vmcnt(0)
	v_cvt_f32_f16_e32 v226, v228
	v_cvt_f32_f16_sdwa v227, v228 dst_sel:DWORD dst_unused:UNUSED_PAD src0_sel:WORD_1
	v_cvt_f32_f16_e32 v228, v229
	v_cvt_f32_f16_sdwa v229, v229 dst_sel:DWORD dst_unused:UNUSED_PAD src0_sel:WORD_1
	ds_read_b128 v[114:117], v154
	ds_read_b128 v[118:121], v154 offset:16
	v_pk_mul_f32 v[178:179], v[178:179], v[242:243] op_sel_hi:[1,0]
	v_pk_mul_f32 v[180:181], v[180:181], v[242:243] op_sel_hi:[1,0]
	v_pk_mul_f32 v[182:183], v[182:183], v[242:243] op_sel_hi:[1,0]
	v_lshl_add_u64 v[110:111], v[108:109], 0, v[72:73]
	v_pk_mul_f32 v[188:189], v[188:189], v[242:243] op_sel_hi:[1,0]
	v_pk_mul_f32 v[190:191], v[190:191], v[242:243] op_sel_hi:[1,0]
	v_pk_mul_f32 v[168:169], v[168:169], v[242:243] op_sel_hi:[1,0]
	v_pk_mul_f32 v[170:171], v[170:171], v[242:243] op_sel_hi:[1,0]
	v_pk_fma_f32 v[192:193], v[22:23], v[192:193], v[30:31]
	v_pk_fma_f32 v[178:179], v[20:21], v[178:179], v[28:29]
	v_pk_fma_f32 v[182:183], v[14:15], v[182:183], v[26:27]
	v_pk_fma_f32 v[180:181], v[12:13], v[180:181], v[24:25]
	v_lshl_add_u64 v[112:113], v[110:111], 0, v[74:75]
	v_pk_fma_f32 v[190:191], v[6:7], v[190:191], v[18:19]
	v_pk_fma_f32 v[188:189], v[4:5], v[188:189], v[16:17]
	v_pk_fma_f32 v[170:171], v[2:3], v[170:171], v[10:11]
	v_pk_fma_f32 v[168:169], v[0:1], v[168:169], v[8:9]
	v_pk_fma_f32 v[164:165], v[164:165], v[102:103], v[178:179] op_sel_hi:[1,0,1]
	v_pk_fma_f32 v[178:179], v[212:213], v[102:103], v[192:193] op_sel_hi:[1,0,1]
	v_pk_fma_f32 v[180:181], v[218:219], v[102:103], v[180:181] op_sel_hi:[1,0,1]
	v_pk_fma_f32 v[182:183], v[204:205], v[102:103], v[182:183] op_sel_hi:[1,0,1]
	v_lshl_add_u64 v[236:237], v[112:113], 0, v[72:73]
	v_pk_fma_f32 v[188:189], v[102:103], v[210:211], v[188:189] op_sel_hi:[0,1,1]
	v_pk_fma_f32 v[190:191], v[102:103], v[220:221], v[190:191] op_sel_hi:[0,1,1]
	v_pk_fma_f32 v[168:169], v[102:103], v[226:227], v[168:169] op_sel_hi:[0,1,1]
	v_pk_fma_f32 v[170:171], v[102:103], v[228:229], v[170:171] op_sel_hi:[0,1,1]
	v_pk_mul_f32 v[134:135], v[178:179], v[134:135]
	v_pk_mul_f32 v[128:129], v[164:165], v[128:129]
	v_pk_mul_f32 v[138:139], v[182:183], v[138:139]
	v_pk_mul_f32 v[132:133], v[180:181], v[132:133]
	v_lshl_add_u64 v[200:201], v[236:237], 0, v[74:75]
	v_pk_mul_f32 v[140:141], v[190:191], v[144:145]
	v_pk_mul_f32 v[136:137], v[188:189], v[136:137]
	v_pk_mul_f32 v[142:143], v[170:171], v[148:149]
	v_pk_mul_f32 v[144:145], v[168:169], v[146:147]
	v_cvt_pk_bf16_f32 v122, v128, v129
	v_cvt_pk_bf16_f32 v123, v134, v135
	v_cvt_pk_bf16_f32 v124, v132, v133
	v_cvt_pk_bf16_f32 v125, v138, v139
	s_waitcnt lgkmcnt(1)
	global_store_dwordx4 v[92:93], v[114:117], off
	s_waitcnt lgkmcnt(0)
	global_store_dwordx4 v[92:93], v[118:121], off offset:16
	v_lshl_add_u64 v[184:185], v[200:201], 0, v[72:73]
	v_cvt_pk_bf16_f32 v126, v136, v137
	v_cvt_pk_bf16_f32 v127, v140, v141
	v_cvt_pk_bf16_f32 v128, v144, v145
	v_cvt_pk_bf16_f32 v129, v142, v143
	s_waitcnt lgkmcnt(0)
	ds_write_b128 v153, v[122:125]
	ds_write_b128 v153, v[126:129] offset:16
	v_lshl_add_u64 v[238:239], v[184:185], 0, v[74:75]
	global_load_dwordx4 v[114:117], v[94:95], off offset:256
	global_load_dwordx4 v[118:121], v[94:95], off offset:384
	global_load_dwordx4 v[122:125], v[110:111], off offset:448
	global_load_dwordx4 v[126:129], v[236:237], off offset:512
	global_load_dwordx4 v[130:133], v[184:185], off offset:576
	global_load_dwordx2 v[146:147], v[104:105], off
	global_load_dwordx2 v[148:149], v[108:109], off offset:640
	global_load_dwordx2 v[160:161], v[104:105], off offset:32
	global_load_dwordx2 v[162:163], v[112:113], off offset:672
	global_load_dwordx2 v[164:165], v[104:105], off offset:64
	global_load_dwordx2 v[168:169], v[200:201], off offset:704
	s_nop 0
	global_load_dwordx4 v[92:95], v[94:95], off offset:320
	s_nop 0
	global_load_dwordx2 v[170:171], v[104:105], off offset:96
	global_load_dwordx2 v[172:173], v[238:239], off offset:736
	s_nop 0
	global_load_dword v86, v[86:87], off offset:8
	s_waitcnt lgkmcnt(0)
	ds_read_b128 v[108:111], v154
	ds_read_b128 v[134:137], v154 offset:16
	v_lshl_add_u64 v[98:99], v[90:91], 0, v[74:75]
	v_lshl_add_u64 v[96:97], v[106:107], 0, v[76:77]
	v_lshl_add_u64 v[106:107], v[98:99], 0, v[72:73]
	v_lshl_add_u64 v[234:235], v[106:107], 0, v[74:75]
	v_lshl_add_u64 v[196:197], v[234:235], 0, v[72:73]
	s_waitcnt lgkmcnt(1)
	global_store_dwordx4 v[100:101], v[108:111], off
	s_waitcnt lgkmcnt(0)
	global_store_dwordx4 v[100:101], v[134:137], off offset:16
	v_lshl_add_u64 v[230:231], v[196:197], 0, v[74:75]
	s_waitcnt lgkmcnt(0)
	v_lshl_add_u64 v[232:233], v[230:231], 0, v[72:73]
	global_load_dwordx4 v[108:111], v[90:91], off offset:256
	global_load_dwordx4 v[134:137], v[90:91], off offset:384
	s_nop 0
	global_load_dwordx4 v[104:107], v[106:107], off offset:448
	s_nop 0
	global_load_dwordx4 v[138:141], v[196:197], off offset:512
	global_load_dwordx4 v[142:145], v[232:233], off offset:576
	global_load_dwordx2 v[174:175], v[96:97], off
	global_load_dwordx2 v[176:177], v[98:99], off offset:640
	global_load_dwordx2 v[178:179], v[96:97], off offset:32
	s_waitcnt vmcnt(23)
	v_mfma_f32_16x16x32_bf16 v[98:101], v[48:51], v[114:117], v[118:121]
	global_load_dwordx2 v[180:181], v[234:235], off offset:672
	v_lshl_add_u64 v[240:241], v[232:233], 0, v[74:75]
	s_or_b32 s8, s8, 48
	s_waitcnt vmcnt(23)
	v_mfma_f32_16x16x32_bf16 v[118:121], v[60:63], v[114:117], v[122:125]
	global_load_dwordx2 v[182:183], v[96:97], off offset:64
	global_load_dwordx2 v[184:185], v[230:231], off offset:704
	s_nop 0
	global_load_dwordx4 v[122:125], v[90:91], off offset:320
	global_load_dwordx2 v[186:187], v[96:97], off offset:96
	global_load_dwordx2 v[188:189], v[240:241], off offset:736
	global_load_dword v84, v[88:89], off offset:8
	s_waitcnt vmcnt(26)
; __device__ __forceinline__ void rwkv_out_ch(const Params& p, LAS unsigned char* ldsw, int ch, int lane) {
;     ...
;     for (int ts = 0; ts < 4; ++ts) {
;         const int sl = ts & 1;
;         if (ts < 3) RO_LOAD(sl ^ 1, ts + 1);
;         f32x4 acc[4];
; #pragma unroll
;         for (int nt = 0; nt < 4; ++nt) acc[nt] = y0B[sl][nt];
; #pragma unroll
;         for (int nt = 0; nt < 4; ++nt)
; #pragma unroll
;             for (int ks = 0; ks < 2; ++ks) acc[nt] = __builtin_amdgcn_mfma_f32_16x16x32_bf16(sf[nt][ks], rbfB[sl][ks], acc[nt], 0, 0, 0);
;         float s_ = 0.f;
; #pragma unroll
;         for (int nt = 0; nt < 4; ++nt) s_ += (acc[nt].x + acc[nt].y) + (acc[nt].z + acc[nt].w);
;         s_ += __shfl_xor(s_, 16); s_ += __shfl_xor(s_, 32);
;         const float mean = s_ * (1.f / 64.f); float q = 0.f;
; #pragma unroll
;         for (int nt = 0; nt < 4; ++nt) { acc[nt] = acc[nt] - mean; q += (acc[nt].x * acc[nt].x + acc[nt].y * acc[nt].y) + (acc[nt].z * acc[nt].z + acc[nt].w * acc[nt].w); }
;         q += __shfl_xor(q, 16); q += __shfl_xor(q, 32);
;         const float rstd = rsqrtf(q * (1.f / 64.f) + 64e-5f), bon = bonB[sl];
	v_lshlrev_b32_e32 v88, 16, v146
	v_mfma_f32_16x16x32_bf16 v[126:129], v[56:59], v[114:117], v[126:129]
	v_and_b32_e32 v89, 0xffff0000, v146
	s_waitcnt vmcnt(25)
	v_cvt_f32_f16_e32 v146, v149
	s_waitcnt vmcnt(23)
	v_cvt_f32_f16_e32 v190, v162
	v_mfma_f32_16x16x32_bf16 v[112:115], v[52:55], v[114:117], v[130:133]
	v_cvt_f32_f16_sdwa v191, v162 dst_sel:DWORD dst_unused:UNUSED_PAD src0_sel:WORD_1
	v_cvt_f32_f16_e32 v162, v163
	v_cvt_f32_f16_sdwa v163, v163 dst_sel:DWORD dst_unused:UNUSED_PAD src0_sel:WORD_1
	s_waitcnt vmcnt(20)
	v_mfma_f32_16x16x32_bf16 v[96:99], v[32:35], v[92:95], v[98:101]
	v_lshlrev_b32_e32 v130, 16, v147
	v_and_b32_e32 v131, 0xffff0000, v147
	v_cvt_f32_f16_e32 v132, v148
	v_mfma_f32_16x16x32_bf16 v[116:119], v[40:43], v[92:95], v[118:121]
	v_cvt_f32_f16_sdwa v133, v148 dst_sel:DWORD dst_unused:UNUSED_PAD src0_sel:WORD_1
	v_cvt_f32_f16_sdwa v147, v149 dst_sel:DWORD dst_unused:UNUSED_PAD src0_sel:WORD_1
	v_cvt_f32_f16_e32 v194, v168
	s_waitcnt vmcnt(13)
	v_mfma_f32_16x16x32_bf16 v[48:51], v[48:51], v[108:111], v[134:137]
	v_cvt_f32_f16_sdwa v195, v168 dst_sel:DWORD dst_unused:UNUSED_PAD src0_sel:WORD_1
	v_cvt_f32_f16_e32 v168, v169
	v_cvt_f32_f16_sdwa v169, v169 dst_sel:DWORD dst_unused:UNUSED_PAD src0_sel:WORD_1
	s_waitcnt vmcnt(12)
	v_mfma_f32_16x16x32_bf16 v[60:63], v[60:63], v[108:111], v[104:107]
	v_mov_b32_e32 v134, v116
	v_mov_b32_e32 v135, v119
	v_lshlrev_b32_e32 v100, 16, v170
	v_mfma_f32_16x16x32_bf16 v[126:129], v[44:47], v[92:95], v[126:129]
	v_and_b32_e32 v101, 0xffff0000, v170
	v_lshlrev_b32_e32 v120, 16, v171
	v_and_b32_e32 v121, 0xffff0000, v171
	v_mfma_f32_16x16x32_bf16 v[90:93], v[36:39], v[92:95], v[112:115]
	v_mov_b32_e32 v94, v97
	v_mov_b32_e32 v95, v98
	s_nop 1
	v_add_f32_e32 v104, v126, v127
	v_mov_b32_e32 v112, v96
	v_mov_b32_e32 v113, v99
	v_mov_b32_e32 v114, v117
	v_mov_b32_e32 v115, v118
	s_waitcnt vmcnt(3)
	v_mfma_f32_16x16x32_bf16 v[32:35], v[32:35], v[122:125], v[48:51]
	s_nop 2
	v_add_f32_e64 v48, v94, v112
	v_add_f32_e64 v49, v95, v113
	v_pk_add_f32 v[50:51], v[114:115], v[134:135]
	v_add_f32_e32 v106, v128, v129
	v_mfma_f32_16x16x32_bf16 v[40:43], v[40:43], v[122:125], v[60:63]
	v_mov_b32_e32 v137, v90
	v_mov_b32_e32 v105, v92
	v_mov_b32_e32 v107, v93
	v_add_f32_e32 v62, v48, v49
	v_pk_add_f32 v[48:49], v[50:51], v[50:51] op_sel:[0,1] op_sel_hi:[1,0]
	v_add_f32_e32 v136, 0, v62
	v_mov_b32_e32 v49, v91
	v_mfma_f32_16x16x32_bf16 v[56:59], v[56:59], v[108:111], v[138:141]
	v_add_f32_e64 v60, v104, v106
	v_add_f32_e64 v61, v105, v107
	v_pk_add_f32 v[48:49], v[136:137], v[48:49]
	v_mov_b32_e32 v50, v32
	v_mfma_f32_16x16x32_bf16 v[52:55], v[52:55], v[108:111], v[142:145]
	v_add_f32_e64 v48, v48, v60
	v_add_f32_e64 v49, v49, v61
	v_mov_b32_e32 v51, v35
	v_add_f32_e32 v62, v48, v49
	ds_bpermute_b32 v63, v151, v62
	v_mfma_f32_16x16x32_bf16 v[44:47], v[44:47], v[122:125], v[56:59]
	v_mov_b32_e32 v48, v33
	v_mov_b32_e32 v49, v34
	v_pk_add_f32 v[48:49], v[48:49], v[50:51]
	v_mfma_f32_16x16x32_bf16 v[36:39], v[36:39], v[122:125], v[52:55]
	v_cvt_f32_f16_e32 v170, v172
	s_nop 2
	v_add_f32_e32 v56, v44, v45
	v_add_f32_e32 v58, v46, v47
	v_mov_b32_e32 v52, v41
	v_mov_b32_e32 v53, v42
	v_mov_b32_e32 v54, v40
	v_mov_b32_e32 v55, v43
	v_pk_add_f32 v[50:51], v[52:53], v[54:55]
	v_add_f32_e32 v54, v48, v49
	v_pk_add_f32 v[48:49], v[50:51], v[50:51] op_sel:[0,1] op_sel_hi:[1,0]
	v_mov_b32_e32 v61, v36
	v_mov_b32_e32 v57, v38
	v_mov_b32_e32 v59, v39
	v_add_f32_e32 v60, 0, v54
	v_mov_b32_e32 v49, v37
	s_waitcnt lgkmcnt(0)
	v_add_f32_e32 v50, v62, v63
	v_pk_add_f32 v[52:53], v[56:57], v[58:59]
	v_pk_add_f32 v[48:49], v[60:61], v[48:49]
	ds_bpermute_b32 v51, v152, v50
	v_pk_add_f32 v[48:49], v[48:49], v[52:53]
	v_cvt_f32_f16_sdwa v171, v172 dst_sel:DWORD dst_unused:UNUSED_PAD src0_sel:WORD_1
	v_add_f32_e32 v87, v48, v49
	ds_bpermute_b32 v95, v151, v87
	s_waitcnt lgkmcnt(1)
	v_add_f32_e32 v56, v50, v51
	v_fmamk_f32 v49, v56, 0xbc800000, v97
	v_fmamk_f32 v48, v56, 0xbc800000, v96
	v_fmamk_f32 v99, v56, 0xbc800000, v99
	v_fmac_f32_e32 v98, 0xbc800000, v56
	v_fmamk_f32 v51, v56, 0xbc800000, v117
	v_fmamk_f32 v50, v56, 0xbc800000, v116
	v_fmamk_f32 v119, v56, 0xbc800000, v119
	v_fmac_f32_e32 v118, 0xbc800000, v56
	v_fmamk_f32 v53, v56, 0xbc800000, v127
	v_fmamk_f32 v52, v56, 0xbc800000, v126
	v_fmamk_f32 v129, v56, 0xbc800000, v129
	v_fmac_f32_e32 v128, 0xbc800000, v56
	v_fmamk_f32 v55, v56, 0xbc800000, v93
	v_fmamk_f32 v54, v56, 0xbc800000, v92
	v_fmamk_f32 v91, v56, 0xbc800000, v91
	v_fmac_f32_e32 v90, 0xbc800000, v56
	v_pk_mul_f32 v[56:57], v[98:99], v[98:99]
	v_pk_mul_f32 v[58:59], v[48:49], v[48:49]
	v_pk_mul_f32 v[60:61], v[118:119], v[118:119]
	v_pk_mul_f32 v[62:63], v[50:51], v[50:51]
	v_mul_f32_e32 v92, v52, v52
	v_mul_f32_e32 v94, v128, v128
	s_waitcnt lgkmcnt(0)
	v_add_f32_e32 v87, v87, v95
	v_pk_mov_b32 v[96:97], v[58:59], v[56:57] op_sel:[1,0]
	v_mov_b32_e32 v59, v57
	v_pk_mov_b32 v[56:57], v[62:63], v[60:61] op_sel:[1,0]
	v_mov_b32_e32 v63, v61
	v_pk_fma_f32 v[60:61], v[52:53], v[52:53], v[92:93] op_sel_hi:[1,1,0]
	v_pk_fma_f32 v[92:93], v[128:129], v[128:129], v[94:95] op_sel_hi:[1,1,0]
	ds_bpermute_b32 v94, v152, v87
	v_pk_add_f32 v[58:59], v[96:97], v[58:59]
	v_pk_add_f32 v[56:57], v[56:57], v[62:63]
	v_pk_add_f32 v[58:59], v[58:59], v[58:59] op_sel_hi:[0,1]
	v_pk_add_f32 v[56:57], v[56:57], v[56:57] op_sel_hi:[0,1]
	v_mul_f32_e32 v60, v90, v90
	v_mul_f32_e32 v92, v91, v91
	v_mul_f32_e32 v58, v54, v54
	v_mul_f32_e32 v56, v55, v55
	v_pk_add_f32 v[60:61], v[60:61], v[92:93]
	v_pk_add_f32 v[56:57], v[58:59], v[56:57]
	v_cvt_f32_f16_e32 v172, v173
	v_pk_add_f32 v[56:57], v[60:61], v[56:57]
	s_waitcnt lgkmcnt(0)
; #define LDS_WAIT() asm volatile("s_waitcnt lgkmcnt(0)" ::: "memory")
; __device__ __forceinline__ float bflo(unsigned w) { return __uint_as_float(w << 16); }
; __device__ __forceinline__ float bfhi(unsigned w) { return __uint_as_float(w & 0xffff0000u); }
; __device__ __forceinline__ void st_bf4(LAS bf16_t* p, f32x4 v) { u32x2 w; w.x = pk2(v.x, v.y); w.y = pk2(v.z, v.w); *(LAS u32x2*)p = w; }
; __device__ __forceinline__ void rwkv_out_ch(const Params& p, LAS unsigned char* ldsw, int ch, int lane) {
;     ...
;         float s_ = 0.f;
; #pragma unroll
;         for (int nt = 0; nt < 4; ++nt) s_ += (acc[nt].x + acc[nt].y) + (acc[nt].z + acc[nt].w);
;         s_ += __shfl_xor(s_, 16); s_ += __shfl_xor(s_, 32);
;         const float mean = s_ * (1.f / 64.f); float q = 0.f;
; #pragma unroll
;         for (int nt = 0; nt < 4; ++nt) { acc[nt] = acc[nt] - mean; q += (acc[nt].x * acc[nt].x + acc[nt].y * acc[nt].y) + (acc[nt].z * acc[nt].z + acc[nt].w * acc[nt].w); }
;         q += __shfl_xor(q, 16); q += __shfl_xor(q, 32);
;         const float rstd = rsqrtf(q * (1.f / 64.f) + 64e-5f), bon = bonB[sl];
; #pragma unroll
;         for (int nt = 0; nt < 4; ++nt) {
;             const u32x2 gw = gB[sl][nt]; const h16x4 v4 = vB[sl][nt];
;             const f32x4 g = {bflo(gw.x), bfhi(gw.x), bflo(gw.y), bfhi(gw.y)}, vv = {(float)v4[0], (float)v4[1], (float)v4[2], (float)v4[3]};
;             st_bf4(stg + fr * MS + 16 * fq + 4 * nt, (acc[nt] * rstd * lg[nt] + lb[nt] + vv * bon) * g);
;         }
;         LDS_WAIT();
	v_add_f32_e32 v60, v87, v94
	v_add_f32_e32 v87, v56, v57
	ds_bpermute_b32 v95, v151, v87
	v_fmamk_f32 v33, v60, 0xbc800000, v33
	v_fmamk_f32 v32, v60, 0xbc800000, v32
	v_fmamk_f32 v35, v60, 0xbc800000, v35
	v_fmac_f32_e32 v34, 0xbc800000, v60
	v_fmamk_f32 v57, v60, 0xbc800000, v41
	v_fmamk_f32 v56, v60, 0xbc800000, v40
	v_fmamk_f32 v43, v60, 0xbc800000, v43
	v_fmac_f32_e32 v42, 0xbc800000, v60
	v_fmamk_f32 v45, v60, 0xbc800000, v45
	v_fmamk_f32 v44, v60, 0xbc800000, v44
	v_fmamk_f32 v47, v60, 0xbc800000, v47
	v_fmac_f32_e32 v46, 0xbc800000, v60
	v_fmamk_f32 v59, v60, 0xbc800000, v39
	v_fmamk_f32 v58, v60, 0xbc800000, v38
	v_fmamk_f32 v37, v60, 0xbc800000, v37
	v_fmac_f32_e32 v36, 0xbc800000, v60
	v_pk_mul_f32 v[38:39], v[34:35], v[34:35]
	v_pk_mul_f32 v[40:41], v[32:33], v[32:33]
	v_pk_mul_f32 v[60:61], v[42:43], v[42:43]
	v_pk_mul_f32 v[62:63], v[56:57], v[56:57]
	v_pk_mov_b32 v[96:97], v[40:41], v[38:39] op_sel:[1,0]
	v_mov_b32_e32 v41, v39
	v_pk_mov_b32 v[38:39], v[62:63], v[60:61] op_sel:[1,0]
	v_mov_b32_e32 v63, v61
	v_mul_f32_e32 v92, v44, v44
	v_mul_f32_e32 v94, v46, v46
	v_pk_add_f32 v[40:41], v[96:97], v[40:41]
	v_pk_add_f32 v[38:39], v[38:39], v[62:63]
	v_pk_fma_f32 v[60:61], v[44:45], v[44:45], v[92:93] op_sel_hi:[1,1,0]
	s_waitcnt lgkmcnt(0)
	v_pk_fma_f32 v[92:93], v[46:47], v[46:47], v[94:95] op_sel_hi:[1,1,0]
	v_pk_add_f32 v[40:41], v[40:41], v[40:41] op_sel_hi:[0,1]
	v_pk_add_f32 v[38:39], v[38:39], v[38:39] op_sel_hi:[0,1]
	v_mul_f32_e32 v60, v36, v36
	v_mul_f32_e32 v92, v37, v37
	v_mul_f32_e32 v40, v58, v58
	v_mul_f32_e32 v38, v59, v59
	v_pk_add_f32 v[60:61], v[60:61], v[92:93]
	v_add_f32_e32 v62, v87, v95
	v_pk_add_f32 v[38:39], v[40:41], v[38:39]
	ds_bpermute_b32 v40, v152, v62
	v_pk_add_f32 v[38:39], v[60:61], v[38:39]
	v_cvt_f32_f16_sdwa v173, v173 dst_sel:DWORD dst_unused:UNUSED_PAD src0_sel:WORD_1
	v_add_f32_e32 v38, v38, v39
	ds_bpermute_b32 v39, v151, v38
	s_waitcnt lgkmcnt(1)
	v_add_f32_e32 v40, v62, v40
	v_fmamk_f32 v40, v40, 0x3c800000, v158
	v_mul_f32_e32 v41, 0x4b800000, v40
	v_cmp_gt_f32_e32 vcc, s34, v40
	s_waitcnt lgkmcnt(0)
	v_add_f32_e32 v38, v38, v39
	v_lshlrev_b32_e32 v148, 16, v160
	v_cndmask_b32_e32 v39, v40, v41, vcc
	ds_bpermute_b32 v40, v152, v38
	v_rsq_f32_e32 v39, v39
	v_and_b32_e32 v149, 0xffff0000, v160
	v_lshlrev_b32_e32 v160, 16, v161
	v_and_b32_e32 v161, 0xffff0000, v161
	v_mul_f32_e32 v41, 0x45800000, v39
	s_waitcnt lgkmcnt(0)
	v_add_f32_e32 v40, v38, v40
	v_cndmask_b32_e32 v38, v39, v41, vcc
	v_fmamk_f32 v87, v40, 0x3c800000, v158
	v_pk_mul_f32 v[40:41], v[48:49], v[38:39] op_sel_hi:[1,0]
	v_pk_mul_f32 v[48:49], v[98:99], v[38:39] op_sel_hi:[1,0]
	v_pk_mul_f32 v[50:51], v[50:51], v[38:39] op_sel_hi:[1,0]
	v_pk_mul_f32 v[60:61], v[118:119], v[38:39] op_sel_hi:[1,0]
	v_mul_f32_e32 v92, 0x4b800000, v87
	v_cmp_gt_f32_e32 vcc, s34, v87
	v_pk_mul_f32 v[52:53], v[52:53], v[38:39] op_sel_hi:[1,0]
	v_pk_mul_f32 v[62:63], v[128:129], v[38:39] op_sel_hi:[1,0]
	v_pk_mul_f32 v[90:91], v[90:91], v[38:39] op_sel_hi:[1,0]
	v_pk_mul_f32 v[38:39], v[54:55], v[38:39] op_sel_hi:[1,0]
	v_pk_fma_f32 v[48:49], v[22:23], v[48:49], v[30:31]
	v_pk_fma_f32 v[40:41], v[20:21], v[40:41], v[28:29]
	v_pk_fma_f32 v[54:55], v[14:15], v[60:61], v[26:27]
	v_pk_fma_f32 v[50:51], v[12:13], v[50:51], v[24:25]
	v_cndmask_b32_e32 v87, v87, v92, vcc
	v_pk_fma_f32 v[60:61], v[6:7], v[62:63], v[18:19]
	v_pk_fma_f32 v[52:53], v[4:5], v[52:53], v[16:17]
	v_pk_fma_f32 v[38:39], v[2:3], v[38:39], v[10:11]
	v_pk_fma_f32 v[62:63], v[0:1], v[90:91], v[8:9]
	v_pk_fma_f32 v[40:41], v[132:133], v[86:87], v[40:41] op_sel_hi:[1,0,1]
	v_pk_fma_f32 v[48:49], v[146:147], v[86:87], v[48:49] op_sel_hi:[1,0,1]
	v_pk_fma_f32 v[50:51], v[190:191], v[86:87], v[50:51] op_sel_hi:[1,0,1]
	v_pk_fma_f32 v[54:55], v[162:163], v[86:87], v[54:55] op_sel_hi:[1,0,1]
	v_rsq_f32_e32 v90, v87
	v_lshlrev_b32_e32 v192, 16, v164
	v_and_b32_e32 v193, 0xffff0000, v164
	v_lshlrev_b32_e32 v164, 16, v165
	v_and_b32_e32 v165, 0xffff0000, v165
	v_pk_fma_f32 v[52:53], v[86:87], v[194:195], v[52:53] op_sel_hi:[0,1,1]
	v_pk_fma_f32 v[60:61], v[86:87], v[168:169], v[60:61] op_sel_hi:[0,1,1]
	v_pk_fma_f32 v[62:63], v[86:87], v[170:171], v[62:63] op_sel_hi:[0,1,1]
	v_pk_fma_f32 v[38:39], v[86:87], v[172:173], v[38:39] op_sel_hi:[0,1,1]
	v_pk_mul_f32 v[48:49], v[48:49], v[130:131]
	v_pk_mul_f32 v[40:41], v[40:41], v[88:89]
	v_pk_mul_f32 v[54:55], v[54:55], v[160:161]
	v_pk_mul_f32 v[50:51], v[50:51], v[148:149]
	v_pk_mul_f32 v[60:61], v[60:61], v[164:165]
	v_pk_mul_f32 v[52:53], v[52:53], v[192:193]
	v_pk_mul_f32 v[86:87], v[38:39], v[120:121]
	v_pk_mul_f32 v[62:63], v[62:63], v[100:101]
	v_cvt_pk_bf16_f32 v38, v40, v41
	v_cvt_pk_bf16_f32 v39, v48, v49
	v_cvt_pk_bf16_f32 v40, v50, v51
	v_cvt_pk_bf16_f32 v41, v54, v55
	v_cvt_pk_bf16_f32 v48, v52, v53
	v_cvt_pk_bf16_f32 v49, v60, v61
	v_cvt_pk_bf16_f32 v50, v62, v63
	v_cvt_pk_bf16_f32 v51, v86, v87
	ds_write_b128 v153, v[38:41]
	ds_write_b128 v153, v[48:51] offset:16
	v_lshlrev_b32_e32 v108, 16, v174
	v_and_b32_e32 v109, 0xffff0000, v174
	v_lshlrev_b32_e32 v110, 16, v175
	v_and_b32_e32 v111, 0xffff0000, v175
	v_cvt_f32_f16_e32 v138, v176
	v_cvt_f32_f16_sdwa v139, v176 dst_sel:DWORD dst_unused:UNUSED_PAD src0_sel:WORD_1
	v_cvt_f32_f16_e32 v140, v177
	v_cvt_f32_f16_sdwa v141, v177 dst_sel:DWORD dst_unused:UNUSED_PAD src0_sel:WORD_1
	v_cvt_f32_f16_e32 v174, v180
	v_cvt_f32_f16_sdwa v175, v180 dst_sel:DWORD dst_unused:UNUSED_PAD src0_sel:WORD_1
	v_cvt_f32_f16_e32 v176, v181
	v_cvt_f32_f16_sdwa v177, v181 dst_sel:DWORD dst_unused:UNUSED_PAD src0_sel:WORD_1
	s_waitcnt lgkmcnt(0)
; #define LAS __attribute__((address_space(3)))
; #define LDS_WAIT() asm volatile("s_waitcnt lgkmcnt(0)" ::: "memory")
; __device__ __forceinline__ float bflo(unsigned w) { return __uint_as_float(w << 16); }
; __device__ __forceinline__ float bfhi(unsigned w) { return __uint_as_float(w & 0xffff0000u); }
; __device__ __forceinline__ void st_bf4(LAS bf16_t* p, f32x4 v) { u32x2 w; w.x = pk2(v.x, v.y); w.y = pk2(v.z, v.w); *(LAS u32x2*)p = w; }
; #define lane (lane_now())
; __device__ __forceinline__ void rwkv_out_ch(const Params& p, LAS unsigned char* ldsw, int ch, int lane) {
;     ...
; #pragma unroll
;         for (int nt = 0; nt < 4; ++nt) {
;             const u32x2 gw = gB[sl][nt]; const h16x4 v4 = vB[sl][nt];
;             const f32x4 g = {bflo(gw.x), bfhi(gw.x), bflo(gw.y), bfhi(gw.y)}, vv = {(float)v4[0], (float)v4[1], (float)v4[2], (float)v4[3]};
;             st_bf4(stg + fr * MS + 16 * fq + 4 * nt, (acc[nt] * rstd * lg[nt] + lb[nt] + vv * bon) * g);
;         }
;         LDS_WAIT();
;         {
;             const int row = lane >> 2, pc = (lane & 3) * 16;
;             const u32x4 w0 = *(const LAS u32x4*)(stg + row * MS + pc), w1 = *(const LAS u32x4*)(stg + row * MS + pc + 8);
;             bf16_t* dst = MIX + ((size_t)b * SEQ + c * 64 + 16 * ts + row) * DM + h * 64 + pc;
;             *(u32x4*)dst = w0; *(u32x4*)(dst + 8) = w1;
;         }
;         LDS_WAIT();
;     }
; __global__ void __launch_bounds__(512, 2) mega_fwd(Params p) {
;     ...
;     { const int lane9 = lane; LAS unsigned char* ldsw = lds + wave * (16 * MS * 2); for (int it = gw; it < 32 * 128; it += ngw) rwkv_out_ch(p, ldsw, it, lane9); }
	v_mul_f32_e32 v52, 0x45800000, v90
	v_lshlrev_b32_e32 v142, 16, v178
	v_and_b32_e32 v143, 0xffff0000, v178
	v_lshlrev_b32_e32 v144, 16, v179
	v_and_b32_e32 v145, 0xffff0000, v179
	v_lshlrev_b32_e32 v178, 16, v182
	v_and_b32_e32 v179, 0xffff0000, v182
	v_lshlrev_b32_e32 v180, 16, v183
	v_and_b32_e32 v181, 0xffff0000, v183
	v_cvt_f32_f16_e32 v182, v184
	v_cvt_f32_f16_sdwa v183, v184 dst_sel:DWORD dst_unused:UNUSED_PAD src0_sel:WORD_1
	v_cvt_f32_f16_e32 v184, v185
	v_cvt_f32_f16_sdwa v185, v185 dst_sel:DWORD dst_unused:UNUSED_PAD src0_sel:WORD_1
	s_waitcnt vmcnt(1)
	v_cvt_f32_f16_e32 v198, v188
	v_cvt_f32_f16_sdwa v199, v188 dst_sel:DWORD dst_unused:UNUSED_PAD src0_sel:WORD_1
	v_cvt_f32_f16_e32 v188, v189
	v_cvt_f32_f16_sdwa v189, v189 dst_sel:DWORD dst_unused:UNUSED_PAD src0_sel:WORD_1
	ds_read_b128 v[38:41], v154
	ds_read_b128 v[48:51], v154 offset:16
	v_cndmask_b32_e32 v52, v90, v52, vcc
	v_pk_mul_f32 v[32:33], v[32:33], v[52:53] op_sel_hi:[1,0]
	v_pk_mul_f32 v[34:35], v[34:35], v[52:53] op_sel_hi:[1,0]
	v_pk_mul_f32 v[54:55], v[56:57], v[52:53] op_sel_hi:[1,0]
	v_pk_mul_f32 v[42:43], v[42:43], v[52:53] op_sel_hi:[1,0]
	v_pk_mul_f32 v[44:45], v[44:45], v[52:53] op_sel_hi:[1,0]
	v_pk_mul_f32 v[46:47], v[46:47], v[52:53] op_sel_hi:[1,0]
	v_pk_mul_f32 v[36:37], v[36:37], v[52:53] op_sel_hi:[1,0]
	v_pk_mul_f32 v[52:53], v[58:59], v[52:53] op_sel_hi:[1,0]
	v_pk_fma_f32 v[22:23], v[22:23], v[34:35], v[30:31]
	v_pk_fma_f32 v[20:21], v[20:21], v[32:33], v[28:29]
	v_pk_fma_f32 v[14:15], v[14:15], v[42:43], v[26:27]
	v_pk_fma_f32 v[12:13], v[12:13], v[54:55], v[24:25]
	v_pk_fma_f32 v[6:7], v[6:7], v[46:47], v[18:19]
	v_pk_fma_f32 v[4:5], v[4:5], v[44:45], v[16:17]
	v_pk_fma_f32 v[2:3], v[2:3], v[52:53], v[10:11]
	v_pk_fma_f32 v[0:1], v[0:1], v[36:37], v[8:9]
	s_waitcnt vmcnt(0)
	v_pk_fma_f32 v[8:9], v[138:139], v[84:85], v[20:21] op_sel_hi:[1,0,1]
	v_pk_fma_f32 v[10:11], v[140:141], v[84:85], v[22:23] op_sel_hi:[1,0,1]
	v_pk_fma_f32 v[12:13], v[174:175], v[84:85], v[12:13] op_sel_hi:[1,0,1]
	v_pk_fma_f32 v[14:15], v[176:177], v[84:85], v[14:15] op_sel_hi:[1,0,1]
	v_lshlrev_b32_e32 v196, 16, v186
	v_and_b32_e32 v197, 0xffff0000, v186
	v_lshlrev_b32_e32 v186, 16, v187
	v_and_b32_e32 v187, 0xffff0000, v187
	v_pk_fma_f32 v[4:5], v[84:85], v[182:183], v[4:5] op_sel_hi:[0,1,1]
	v_pk_fma_f32 v[6:7], v[84:85], v[184:185], v[6:7] op_sel_hi:[0,1,1]
	v_pk_fma_f32 v[0:1], v[84:85], v[198:199], v[0:1] op_sel_hi:[0,1,1]
	v_pk_fma_f32 v[2:3], v[84:85], v[188:189], v[2:3] op_sel_hi:[0,1,1]
	v_pk_mul_f32 v[10:11], v[10:11], v[110:111]
	v_pk_mul_f32 v[8:9], v[8:9], v[108:109]
	v_pk_mul_f32 v[14:15], v[14:15], v[144:145]
	v_pk_mul_f32 v[12:13], v[12:13], v[142:143]
	v_pk_mul_f32 v[6:7], v[6:7], v[180:181]
	v_pk_mul_f32 v[4:5], v[4:5], v[178:179]
	v_pk_mul_f32 v[16:17], v[2:3], v[186:187]
	v_pk_mul_f32 v[18:19], v[0:1], v[196:197]
	s_waitcnt lgkmcnt(1)
	global_store_dwordx4 v[82:83], v[38:41], off
	s_waitcnt lgkmcnt(0)
	global_store_dwordx4 v[82:83], v[48:51], off offset:16
	v_cvt_pk_bf16_f32 v0, v8, v9
	v_cvt_pk_bf16_f32 v1, v10, v11
	v_cvt_pk_bf16_f32 v2, v12, v13
	v_cvt_pk_bf16_f32 v3, v14, v15
	v_cvt_pk_bf16_f32 v4, v4, v5
	v_cvt_pk_bf16_f32 v5, v6, v7
	v_cvt_pk_bf16_f32 v6, v18, v19
	v_cvt_pk_bf16_f32 v7, v16, v17
	s_waitcnt lgkmcnt(0)
	ds_write_b128 v153, v[0:3]
	ds_write_b128 v153, v[4:7] offset:16
	s_waitcnt lgkmcnt(0)
	ds_read_b128 v[0:3], v154
	ds_read_b128 v[4:7], v154 offset:16
	v_lshl_add_u64 v[8:9], v[78:79], 0, s[8:9]
	v_lshlrev_b64 v[8:9], 11, v[8:9]
	v_lshl_add_u64 v[8:9], v[80:81], 0, v[8:9]
	s_waitcnt lgkmcnt(1)
	global_store_dwordx4 v[8:9], v[0:3], off
	s_waitcnt lgkmcnt(0)
	global_store_dwordx4 v[8:9], v[4:7], off offset:16
	s_waitcnt lgkmcnt(0)
	s_add_i32 s35, s35, s84
	s_add_i32 s28, s28, s29
	s_cmp_ge_i32 s35, s98
	s_cbranch_scc0 .LBB0_1098
	s_mov_b32 s84, s101
